# sample-row norm phases wait on a split-unit counter instead of a grid barrier (8 barriers fewer)
# baseline (speedup 1.0000x reference)
;     __device__ __forceinline__ void operator()(const Acc& acc, const Unit& u, int wr, int wc, int fr, int fq) const {
;     ...
;                     for (int n = 0; n < 2; ++n) { const int col = u.pn * 256 + bj * 128 + wc * 32 + n * 16 + fq * 4;
;                         const f32x4 ga = *(const f32x4*)(gp + col) * acc[ai][bj][m][n];
;                         if (u.split) { *(f32x4*)(part + ((size_t)(u.k0 >> 8) * MS + (row - MP)) * D + col) = ga;
;                         } else *(f32x4*)(X + (size_t)row * D + col) = *(const f32x4*)(base + col) + ga; } }
.Lepi_out_split:
	s_mov_b32 s66, 0x18000
	s_mov_b32 s67, 0
	s_mov_b32 s68, 0x78000
	s_mov_b32 s69, 0
	v_add_u32_e32 v207, 0xffffc000, v207
	s_lshr_b32 s2, s12, 8
	s_lshl_b32 s2, s2, 21
	s_add_u32 s2, s53, s2
	s_addc_u32 s3, s54, 0
	v_lshlrev_b32_e32 v159, 2, v159
	v_lshl_add_u32 v196, v207, 12, v159
	v_lshl_add_u64 v[146:147], v[196:197], 0, s[2:3]
	v_lshrrev_b32_e32 v207, 2, v207
	v_add_u32_e32 v207, 4, v207
	v_mad_u32_u24 v196, v207, s80, v159
	v_lshl_add_u64 v[144:145], v[196:197], 0, s[18:19]
	global_load_dwordx4 v[208:211], v[144:145], off
	global_load_dwordx4 v[212:215], v[144:145], off offset:64
	global_load_dwordx4 v[216:219], v[144:145], off offset:512
	global_load_dwordx4 v[220:223], v[144:145], off offset:576
	v_lshl_add_u64 v[144:145], v[144:145], 0, s[66:67]
	global_load_dwordx4 v[224:227], v[144:145], off
	global_load_dwordx4 v[228:231], v[144:145], off offset:64
	global_load_dwordx4 v[232:235], v[144:145], off offset:512
	global_load_dwordx4 v[236:239], v[144:145], off offset:576
	v_lshl_add_u64 v[144:145], v[144:145], 0, s[66:67]
	global_load_dwordx4 v[240:243], v[144:145], off
	global_load_dwordx4 v[244:247], v[144:145], off offset:64
	global_load_dwordx4 v[248:251], v[144:145], off offset:512
	global_load_dwordx4 v[184:187], v[144:145], off offset:576
	v_lshl_add_u64 v[144:145], v[144:145], 0, s[66:67]
	s_waitcnt vmcnt(8)
	v_pk_mul_f32 v[126:127], v[126:127], v[210:211]
	v_pk_mul_f32 v[124:125], v[124:125], v[208:209]
	v_pk_mul_f32 v[122:123], v[122:123], v[214:215]
	v_pk_mul_f32 v[120:121], v[120:121], v[212:213]
	v_pk_mul_f32 v[118:119], v[118:119], v[218:219]
	v_pk_mul_f32 v[116:117], v[116:117], v[216:217]
	v_pk_mul_f32 v[114:115], v[114:115], v[222:223]
	v_pk_mul_f32 v[112:113], v[112:113], v[220:221]
	global_store_dwordx4 v[146:147], v[124:127], off sc0 sc1
	global_store_dwordx4 v[146:147], v[120:123], off offset:64 sc0 sc1
	global_store_dwordx4 v[146:147], v[116:119], off offset:512 sc0 sc1
	global_store_dwordx4 v[146:147], v[112:115], off offset:576 sc0 sc1
	v_lshl_add_u64 v[146:147], v[146:147], 0, s[70:71]
	global_load_dwordx4 v[208:211], v[144:145], off
	global_load_dwordx4 v[212:215], v[144:145], off offset:64
	global_load_dwordx4 v[216:219], v[144:145], off offset:512
	global_load_dwordx4 v[220:223], v[144:145], off offset:576
	v_lshl_add_u64 v[144:145], v[144:145], 0, s[68:69]
	s_waitcnt vmcnt(12)
	v_pk_mul_f32 v[110:111], v[110:111], v[226:227]
	v_pk_mul_f32 v[108:109], v[108:109], v[224:225]
	v_pk_mul_f32 v[106:107], v[106:107], v[230:231]
	v_pk_mul_f32 v[104:105], v[104:105], v[228:229]
	v_pk_mul_f32 v[102:103], v[102:103], v[234:235]
	v_pk_mul_f32 v[100:101], v[100:101], v[232:233]
	v_pk_mul_f32 v[98:99], v[98:99], v[238:239]
	v_pk_mul_f32 v[96:97], v[96:97], v[236:237]
	global_store_dwordx4 v[146:147], v[108:111], off sc0 sc1
	global_store_dwordx4 v[146:147], v[104:107], off offset:64 sc0 sc1
	global_store_dwordx4 v[146:147], v[100:103], off offset:512 sc0 sc1
	global_store_dwordx4 v[146:147], v[96:99], off offset:576 sc0 sc1
	v_lshl_add_u64 v[146:147], v[146:147], 0, s[70:71]
	global_load_dwordx4 v[224:227], v[144:145], off
	global_load_dwordx4 v[228:231], v[144:145], off offset:64
	global_load_dwordx4 v[232:235], v[144:145], off offset:512
	global_load_dwordx4 v[236:239], v[144:145], off offset:576
	v_lshl_add_u64 v[144:145], v[144:145], 0, s[66:67]
	s_waitcnt vmcnt(16)
	v_pk_mul_f32 v[94:95], v[94:95], v[242:243]
	v_pk_mul_f32 v[92:93], v[92:93], v[240:241]
	v_pk_mul_f32 v[90:91], v[90:91], v[246:247]
	v_pk_mul_f32 v[88:89], v[88:89], v[244:245]
	v_pk_mul_f32 v[86:87], v[86:87], v[250:251]
	v_pk_mul_f32 v[84:85], v[84:85], v[248:249]
	v_pk_mul_f32 v[82:83], v[82:83], v[186:187]
	v_pk_mul_f32 v[80:81], v[80:81], v[184:185]
	global_store_dwordx4 v[146:147], v[92:95], off sc0 sc1
	global_store_dwordx4 v[146:147], v[88:91], off offset:64 sc0 sc1
	global_store_dwordx4 v[146:147], v[84:87], off offset:512 sc0 sc1
	global_store_dwordx4 v[146:147], v[80:83], off offset:576 sc0 sc1
	v_lshl_add_u64 v[146:147], v[146:147], 0, s[70:71]
	global_load_dwordx4 v[240:243], v[144:145], off
	global_load_dwordx4 v[244:247], v[144:145], off offset:64
	global_load_dwordx4 v[248:251], v[144:145], off offset:512
	global_load_dwordx4 v[184:187], v[144:145], off offset:576
	v_lshl_add_u64 v[144:145], v[144:145], 0, s[66:67]
	s_waitcnt vmcnt(16)
;     __device__ __forceinline__ void operator()(const Acc& acc, const Unit& u, int wr, int wc, int fr, int fq) const {
;     ...
;                     for (int n = 0; n < 2; ++n) { const int col = u.pn * 256 + bj * 128 + wc * 32 + n * 16 + fq * 4;
;                         const f32x4 ga = *(const f32x4*)(gp + col) * acc[ai][bj][m][n];
;                         if (u.split) { *(f32x4*)(part + ((size_t)(u.k0 >> 8) * MS + (row - MP)) * D + col) = ga;
;                         } else *(f32x4*)(X + (size_t)row * D + col) = *(const f32x4*)(base + col) + ga; } }
	v_pk_mul_f32 v[78:79], v[78:79], v[210:211]
	v_pk_mul_f32 v[76:77], v[76:77], v[208:209]
	v_pk_mul_f32 v[74:75], v[74:75], v[214:215]
	v_pk_mul_f32 v[72:73], v[72:73], v[212:213]
	v_pk_mul_f32 v[70:71], v[70:71], v[218:219]
	v_pk_mul_f32 v[68:69], v[68:69], v[216:217]
	v_pk_mul_f32 v[66:67], v[66:67], v[222:223]
	v_pk_mul_f32 v[64:65], v[64:65], v[220:221]
	global_store_dwordx4 v[146:147], v[76:79], off sc0 sc1
	global_store_dwordx4 v[146:147], v[72:75], off offset:64 sc0 sc1
	global_store_dwordx4 v[146:147], v[68:71], off offset:512 sc0 sc1
	global_store_dwordx4 v[146:147], v[64:67], off offset:576 sc0 sc1
	v_lshl_add_u64 v[146:147], v[146:147], 0, s[98:99]
	global_load_dwordx4 v[208:211], v[144:145], off
	global_load_dwordx4 v[212:215], v[144:145], off offset:64
	global_load_dwordx4 v[216:219], v[144:145], off offset:512
	global_load_dwordx4 v[220:223], v[144:145], off offset:576
	v_lshl_add_u64 v[144:145], v[144:145], 0, s[66:67]
	s_waitcnt vmcnt(16)
	v_pk_mul_f32 v[62:63], v[62:63], v[226:227]
	v_pk_mul_f32 v[60:61], v[60:61], v[224:225]
	v_pk_mul_f32 v[58:59], v[58:59], v[230:231]
	v_pk_mul_f32 v[56:57], v[56:57], v[228:229]
	v_pk_mul_f32 v[54:55], v[54:55], v[234:235]
	v_pk_mul_f32 v[52:53], v[52:53], v[232:233]
	v_pk_mul_f32 v[50:51], v[50:51], v[238:239]
	v_pk_mul_f32 v[48:49], v[48:49], v[236:237]
	global_store_dwordx4 v[146:147], v[60:63], off sc0 sc1
	global_store_dwordx4 v[146:147], v[56:59], off offset:64 sc0 sc1
	global_store_dwordx4 v[146:147], v[52:55], off offset:512 sc0 sc1
	global_store_dwordx4 v[146:147], v[48:51], off offset:576 sc0 sc1
	v_lshl_add_u64 v[146:147], v[146:147], 0, s[70:71]
	global_load_dwordx4 v[224:227], v[144:145], off
	global_load_dwordx4 v[228:231], v[144:145], off offset:64
	global_load_dwordx4 v[232:235], v[144:145], off offset:512
	global_load_dwordx4 v[236:239], v[144:145], off offset:576
	s_waitcnt vmcnt(16)
	v_pk_mul_f32 v[46:47], v[46:47], v[242:243]
	v_pk_mul_f32 v[44:45], v[44:45], v[240:241]
	v_pk_mul_f32 v[42:43], v[42:43], v[246:247]
	v_pk_mul_f32 v[40:41], v[40:41], v[244:245]
	v_pk_mul_f32 v[38:39], v[38:39], v[250:251]
	v_pk_mul_f32 v[36:37], v[36:37], v[248:249]
	v_pk_mul_f32 v[34:35], v[34:35], v[186:187]
	v_pk_mul_f32 v[32:33], v[32:33], v[184:185]
	global_store_dwordx4 v[146:147], v[44:47], off sc0 sc1
	global_store_dwordx4 v[146:147], v[40:43], off offset:64 sc0 sc1
	global_store_dwordx4 v[146:147], v[36:39], off offset:512 sc0 sc1
	global_store_dwordx4 v[146:147], v[32:35], off offset:576 sc0 sc1
	v_lshl_add_u64 v[146:147], v[146:147], 0, s[70:71]
	s_waitcnt vmcnt(12)
	v_pk_mul_f32 v[30:31], v[30:31], v[210:211]
	v_pk_mul_f32 v[28:29], v[28:29], v[208:209]
	v_pk_mul_f32 v[26:27], v[26:27], v[214:215]
	v_pk_mul_f32 v[24:25], v[24:25], v[212:213]
	v_pk_mul_f32 v[22:23], v[22:23], v[218:219]
	v_pk_mul_f32 v[20:21], v[20:21], v[216:217]
	v_pk_mul_f32 v[18:19], v[18:19], v[222:223]
	v_pk_mul_f32 v[16:17], v[16:17], v[220:221]
	global_store_dwordx4 v[146:147], v[28:31], off sc0 sc1
	global_store_dwordx4 v[146:147], v[24:27], off offset:64 sc0 sc1
	global_store_dwordx4 v[146:147], v[20:23], off offset:512 sc0 sc1
	global_store_dwordx4 v[146:147], v[16:19], off offset:576 sc0 sc1
	v_lshl_add_u64 v[146:147], v[146:147], 0, s[70:71]
	s_waitcnt vmcnt(8)
	v_pk_mul_f32 v[14:15], v[14:15], v[226:227]
	v_pk_mul_f32 v[12:13], v[12:13], v[224:225]
	v_pk_mul_f32 v[10:11], v[10:11], v[230:231]
	v_pk_mul_f32 v[8:9], v[8:9], v[228:229]
	v_pk_mul_f32 v[6:7], v[6:7], v[234:235]
	v_pk_mul_f32 v[4:5], v[4:5], v[232:233]
	v_pk_mul_f32 v[2:3], v[2:3], v[238:239]
	v_pk_mul_f32 v[0:1], v[0:1], v[236:237]
	global_store_dwordx4 v[146:147], v[12:15], off sc0 sc1
	global_store_dwordx4 v[146:147], v[8:11], off offset:64 sc0 sc1
	global_store_dwordx4 v[146:147], v[4:7], off offset:512 sc0 sc1
	global_store_dwordx4 v[146:147], v[0:3], off offset:576 sc0 sc1
	s_waitcnt vmcnt(0)
	s_barrier
	v_readlane_b32 s25, v253, 2
	s_nop 3
	s_cmp_eq_u32 s25, 0
	s_cbranch_scc0 .Lepi_out_noarr
	s_sub_u32 s2, s16, 0x7dffec0
	s_subb_u32 s3, s17, 0
	s_mov_b64 exec, 1
	v_mov_b32_e32 v207, 0
	v_mov_b32_e32 v159, 1
	global_atomic_add v207, v159, s[2:3]
	s_mov_b64 exec, -1
.Lepi_out_noarr:
.Lepi_out_done:
	s_and_b64 vcc, exec, s[0:1]
	s_mov_b64 s[0:1], -1
	s_cbranch_vccnz .LBB0_1421
	s_andn2_b64 vcc, exec, s[14:15]
	s_cbranch_vccnz .LBB0_1420
	s_barrier
	s_branch .LBB0_1420

.LBB0_1651:
	s_add_i32 s22, s73, 5
	s_cmp_ge_i32 s22, s79
	s_branch .LBB0_1705
	s_waitcnt vmcnt(0) lgkmcnt(0)
	s_lshl_b32 s0, s43, 6
	v_sub_u32_e32 v0, 0, v154
	v_cmp_eq_u32_e32 vcc, s0, v0
	s_waitcnt vmcnt(0)
	s_barrier
	s_and_saveexec_b64 s[0:1], vcc
	s_cbranch_execz .LBB0_1704
	v_readlane_b32 s3, v253, 8
	s_getreg_b32 s2, hwreg(HW_REG_XCC_ID, 0, 4)
	s_and_b32 s18, s2, 15
	v_mov_b32_e32 v0, s3
	ds_read_b32 v2, v0
	v_readlane_b32 s3, v253, 9
	s_waitcnt lgkmcnt(0)
	v_cmp_ne_u32_e32 vcc, 0, v2
	v_mov_b32_e32 v0, s3
	ds_read_b32 v0, v0
	s_cbranch_vccnz .LBB0_1668
	s_add_u32 s2, s6, 0x1000
	s_addc_u32 s3, s7, 0
	s_add_u32 s4, s6, 0x1100
	s_addc_u32 s5, s7, 0
	s_add_u32 s8, s6, 0x1200
	s_addc_u32 s9, s7, 0
	s_add_u32 s10, s6, 0x1300
	s_addc_u32 s11, s7, 0
	s_mov_b32 s19, 1
	s_branch .LBB0_1656

; #define INP(i) ((const float*)ld_ptr(pb, (i)))
; template <bool FINAL>
; __device__ __forceinline__ void norm_rows(const float* xp, const float* xs, const float* X, const float* g, const float* sh, const float* sc, bf16_t* XN, float* out, int gw, int NGW, int lane, const float* part, int nsplit) {
;     ...
;         if (nsplit > 0 && row >= MP) {
;             for (int sp = 0; sp < nsplit; ++sp) { const float* pr = part + ((size_t)sp * MS + (row - MP)) * D + 4 * lane;
; #pragma unroll
;                 for (int j = 0; j < 4; ++j) v[j] += *(const f32x4*)(pr + 256 * j); }
; #pragma unroll
;             for (int j = 0; j < 4; ++j) *(f32x4*)((float*)X + (size_t)row * D + 4 * lane + 256 * j) = v[j]; }
; __global__ void __launch_bounds__(512, 2) hybrid_fwd(Params P) {
;     ...
;         norm_rows<false>(nullptr, nullptr, X, INP(10) + l * D, (MOD + (size_t)l * NMODROWS * 6144) + 3072, (MOD + (size_t)l * NMODROWS * 6144) + 4096, XN, nullptr, gw, NGW, lane, (const float*)(ws + WS_PART), D / 256);
.LBB0_1707:
	s_andn2_b64 vcc, exec, s[0:1]
	s_cbranch_vccnz .LBB0_1769
	v_readlane_b32 s1, v253, 7
	v_readlane_b32 s0, v253, 0
	v_readlane_b32 s18, v253, 1
	v_readlane_b32 s12, v253, 2
	v_mov_b32_e32 v0, s1
	v_mbcnt_lo_u32_b32 v44, -1, 0
	v_mbcnt_hi_u32_b32 v44, -1, v44
	ds_read2_b64 v[0:3], v0 offset0:10 offset1:35
	s_lshl_b32 s0, s0, 3
	s_add_i32 s0, s0, s12
	s_add_i32 s0, s0, 0x4000
	s_cmpk_gt_i32 s0, 0x41ff
	s_mov_b32 s13, 0x200000
	s_waitcnt lgkmcnt(0)
	v_readfirstlane_b32 s3, v3
	v_readfirstlane_b32 s2, v2
	v_readfirstlane_b32 s1, v1
	v_readfirstlane_b32 s5, v0
	s_mov_b32 s16, 0x600000
	s_cbranch_scc1 .LBB0_1715
	s_mul_i32 s7, s96, 120
	s_add_i32 s7, s7, 32
	s_mov_b64 exec, 1
	v_mov_b32_e32 v100, 0x140
	s_mov_b32 s8, 0
.Lnw_n2_poll:
	global_load_dword v101, v100, s[2:3] sc1
	s_waitcnt vmcnt(0)
	v_readfirstlane_b32 s9, v101
	s_nop 3
	s_cmp_ge_u32 s9, s7
	s_cbranch_scc1 .Lnw_n2_ok
	s_add_i32 s8, s8, 1
	s_cmp_lt_u32 s8, 0x8000
	s_cbranch_scc0 .Lnw_n2_ok
	s_sleep 1
	s_branch .Lnw_n2_poll
.Lnw_n2_ok:
	s_mov_b64 exec, -1
	s_mul_i32 s74, s96, 0xc6000
	s_lshl_b32 s4, s18, 3
	s_lshl_b64 s[6:7], s[74:75], 2
	s_add_u32 s6, s2, s6
	s_addc_u32 s7, s3, s7
	s_add_u32 s8, s2, 0x7e00000
	s_addc_u32 s9, s3, 0
	s_lshl_b32 s74, s96, 10
	s_lshl_b64 s[10:11], s[74:75], 2
	s_add_u32 s10, s5, s10
	s_addc_u32 s11, s1, s11
	s_ashr_i32 s1, s0, 31
	s_lshl_b64 s[14:15], s[0:1], 12
	v_lshlrev_b32_e32 v12, 2, v44
	s_add_u32 s14, s8, s14
	v_ashrrev_i32_e32 v13, 31, v12
	s_addc_u32 s15, s9, s15
	v_lshlrev_b64 v[14:15], 2, v[12:13]
	v_lshl_add_u64 v[0:1], s[14:15], 0, v[14:15]
	global_load_dwordx4 v[28:31], v[0:1], off
	global_load_dwordx4 v[8:11], v[0:1], off offset:1024
	global_load_dwordx4 v[4:7], v[0:1], off offset:2048
	s_nop 0
	global_load_dwordx4 v[0:3], v[0:1], off offset:3072
	v_lshl_add_u64 v[16:17], s[2:3], 0, v[14:15]
	v_lshl_add_u64 v[34:35], s[8:9], 0, v[14:15]
	v_lshl_add_u64 v[36:37], s[10:11], 0, v[14:15]
	v_lshl_add_u64 v[14:15], s[6:7], 0, v[14:15]
	s_mov_b64 s[6:7], 0x804000
	v_lshl_add_u64 v[38:39], v[14:15], 0, s[6:7]
	s_mov_b64 s[6:7], 0x803000
	v_lshl_add_u64 v[40:41], v[14:15], 0, s[6:7]
	s_lshl_b64 s[6:7], s[0:1], 11
	s_add_u32 s6, s2, s6
	s_addc_u32 s7, s3, s7
	s_mov_b64 s[14:15], 0x13c00000
	v_lshl_add_u64 v[12:13], v[12:13], 1, s[6:7]
	s_mov_b64 s[6:7], 0xc000000
	s_ashr_i32 s5, s4, 31
	v_lshl_add_u64 v[32:33], v[16:17], 0, s[14:15]
	v_lshl_add_u64 v[42:43], v[12:13], 0, s[6:7]
	s_lshl_b64 s[6:7], s[4:5], 11
	s_branch .LBB0_1711

; template <bool FINAL>
; __device__ __forceinline__ void norm_rows(const float* xp, const float* xs, const float* X, const float* g, const float* sh, const float* sc, bf16_t* XN, float* out, int gw, int NGW, int lane, const float* part, int nsplit) {
;     ...
;         if (nsplit > 0 && row >= MP) {
;             for (int sp = 0; sp < nsplit; ++sp) { const float* pr = part + ((size_t)sp * MS + (row - MP)) * D + 4 * lane;
; #pragma unroll
;                 for (int j = 0; j < 4; ++j) v[j] += *(const f32x4*)(pr + 256 * j); }
; #pragma unroll
;             for (int j = 0; j < 4; ++j) *(f32x4*)((float*)X + (size_t)row * D + 4 * lane + 256 * j) = v[j]; }
.LBB0_1713:
	s_add_i32 s74, s0, 0xffffc000
	s_cmpk_lt_i32 s0, 0x4000
	s_cbranch_scc1 .LBB0_1710
	s_lshl_b64 s[14:15], s[74:75], 12
	v_lshl_add_u64 v[94:95], v[32:33], 0, s[14:15]
	v_add_co_u32_e32 v74, vcc, s13, v94
	s_mov_b32 s1, 0x400000
	s_nop 0
	v_addc_co_u32_e32 v75, vcc, 0, v95, vcc
	v_add_co_u32_e32 v90, vcc, s1, v94
	global_load_dwordx4 v[46:49], v[94:95], off sc0 sc1
	global_load_dwordx4 v[50:53], v[94:95], off offset:1024 sc0 sc1
	global_load_dwordx4 v[54:57], v[94:95], off offset:2048 sc0 sc1
	global_load_dwordx4 v[58:61], v[94:95], off offset:3072 sc0 sc1
	v_addc_co_u32_e32 v91, vcc, 0, v95, vcc
	global_load_dwordx4 v[62:65], v[74:75], off sc0 sc1
	global_load_dwordx4 v[66:69], v[74:75], off offset:1024 sc0 sc1
	global_load_dwordx4 v[70:73], v[74:75], off offset:2048 sc0 sc1
	s_nop 0
	global_load_dwordx4 v[74:77], v[74:75], off offset:3072 sc0 sc1
	v_add_co_u32_e32 v106, vcc, s16, v94
	global_load_dwordx4 v[78:81], v[90:91], off sc0 sc1
	global_load_dwordx4 v[82:85], v[90:91], off offset:1024 sc0 sc1
	global_load_dwordx4 v[86:89], v[90:91], off offset:2048 sc0 sc1
	s_nop 0
	global_load_dwordx4 v[90:93], v[90:91], off offset:3072 sc0 sc1
	v_addc_co_u32_e32 v107, vcc, 0, v95, vcc
	global_load_dwordx4 v[94:97], v[106:107], off sc0 sc1
	global_load_dwordx4 v[98:101], v[106:107], off offset:1024 sc0 sc1
	global_load_dwordx4 v[102:105], v[106:107], off offset:2048 sc0 sc1
	s_nop 0
	global_load_dwordx4 v[106:109], v[106:107], off offset:3072 sc0 sc1
	s_mov_b32 s1, s75
	s_lshl_b64 s[14:15], s[0:1], 12
	v_lshl_add_u64 v[110:111], v[34:35], 0, s[14:15]
	s_waitcnt vmcnt(15)
	v_pk_add_f32 v[30:31], v[30:31], v[48:49]
	v_pk_add_f32 v[28:29], v[28:29], v[46:47]
	s_waitcnt vmcnt(14)
	v_pk_add_f32 v[10:11], v[10:11], v[52:53]
	v_pk_add_f32 v[8:9], v[8:9], v[50:51]
	s_waitcnt vmcnt(13)
	v_pk_add_f32 v[6:7], v[6:7], v[56:57]
	v_pk_add_f32 v[4:5], v[4:5], v[54:55]
	s_waitcnt vmcnt(12)
	v_pk_add_f32 v[2:3], v[2:3], v[60:61]
	v_pk_add_f32 v[0:1], v[0:1], v[58:59]
	s_waitcnt vmcnt(11)
	v_pk_add_f32 v[30:31], v[30:31], v[64:65]
	v_pk_add_f32 v[28:29], v[28:29], v[62:63]
	s_waitcnt vmcnt(10)
	v_pk_add_f32 v[8:9], v[8:9], v[66:67]
	v_pk_add_f32 v[10:11], v[10:11], v[68:69]
	s_waitcnt vmcnt(9)
	v_pk_add_f32 v[4:5], v[4:5], v[70:71]
	v_pk_add_f32 v[6:7], v[6:7], v[72:73]
	s_waitcnt vmcnt(8)
	v_pk_add_f32 v[0:1], v[0:1], v[74:75]
	v_pk_add_f32 v[2:3], v[2:3], v[76:77]
	s_waitcnt vmcnt(7)
	v_pk_add_f32 v[30:31], v[30:31], v[80:81]
	v_pk_add_f32 v[28:29], v[28:29], v[78:79]
	s_waitcnt vmcnt(6)
	v_pk_add_f32 v[10:11], v[10:11], v[84:85]
	v_pk_add_f32 v[8:9], v[8:9], v[82:83]
	s_waitcnt vmcnt(5)
	v_pk_add_f32 v[6:7], v[6:7], v[88:89]
	v_pk_add_f32 v[4:5], v[4:5], v[86:87]
	s_waitcnt vmcnt(4)
	v_pk_add_f32 v[2:3], v[2:3], v[92:93]
	v_pk_add_f32 v[0:1], v[0:1], v[90:91]
	s_waitcnt vmcnt(3)
	v_pk_add_f32 v[30:31], v[30:31], v[96:97]
	v_pk_add_f32 v[28:29], v[28:29], v[94:95]
	s_waitcnt vmcnt(2)
	v_pk_add_f32 v[10:11], v[10:11], v[100:101]
	v_pk_add_f32 v[8:9], v[8:9], v[98:99]
	s_waitcnt vmcnt(1)
	v_pk_add_f32 v[6:7], v[6:7], v[104:105]
	v_pk_add_f32 v[4:5], v[4:5], v[102:103]
	s_waitcnt vmcnt(0)
	v_pk_add_f32 v[2:3], v[2:3], v[108:109]
	v_pk_add_f32 v[0:1], v[0:1], v[106:107]
	global_store_dwordx4 v[110:111], v[28:31], off
	global_store_dwordx4 v[110:111], v[8:11], off offset:1024
	global_store_dwordx4 v[110:111], v[4:7], off offset:2048
	global_store_dwordx4 v[110:111], v[0:3], off offset:3072
	s_branch .LBB0_1710

;     __device__ __forceinline__ void operator()(const Acc& acc, const Unit& u, int wr, int wc, int fr, int fq) const {
;     ...
;                     for (int n = 0; n < 2; ++n) { const int col = u.pn * 256 + bj * 128 + wc * 32 + n * 16 + fq * 4;
;                         const f32x4 ga = *(const f32x4*)(gp + col) * acc[ai][bj][m][n];
;                         if (u.split) { *(f32x4*)(part + ((size_t)(u.k0 >> 8) * MS + (row - MP)) * D + col) = ga;
;                         } else *(f32x4*)(X + (size_t)row * D + col) = *(const f32x4*)(base + col) + ga; } }
.Lepi_dn_split:
	s_mov_b32 s66, 0x18000
	s_mov_b32 s67, 0
	s_mov_b32 s68, 0x78000
	s_mov_b32 s69, 0
	v_add_u32_e32 v207, 0xffffc000, v207
	s_lshr_b32 s2, s6, 8
	s_lshl_b32 s2, s2, 21
	s_add_u32 s2, s41, s2
	s_addc_u32 s3, s42, 0
	v_lshlrev_b32_e32 v159, 2, v159
	v_lshl_add_u32 v196, v207, 12, v159
	v_lshl_add_u64 v[146:147], v[196:197], 0, s[2:3]
	v_lshrrev_b32_e32 v207, 2, v207
	v_add_u32_e32 v207, 4, v207
	v_mad_u32_u24 v196, v207, s80, v159
	v_lshl_add_u64 v[144:145], v[196:197], 0, s[12:13]
	global_load_dwordx4 v[208:211], v[144:145], off
	global_load_dwordx4 v[212:215], v[144:145], off offset:64
	global_load_dwordx4 v[216:219], v[144:145], off offset:512
	global_load_dwordx4 v[220:223], v[144:145], off offset:576
	v_lshl_add_u64 v[144:145], v[144:145], 0, s[66:67]
	global_load_dwordx4 v[224:227], v[144:145], off
	global_load_dwordx4 v[228:231], v[144:145], off offset:64
	global_load_dwordx4 v[232:235], v[144:145], off offset:512
	global_load_dwordx4 v[236:239], v[144:145], off offset:576
	v_lshl_add_u64 v[144:145], v[144:145], 0, s[66:67]
	global_load_dwordx4 v[240:243], v[144:145], off
	global_load_dwordx4 v[244:247], v[144:145], off offset:64
	global_load_dwordx4 v[248:251], v[144:145], off offset:512
	global_load_dwordx4 v[184:187], v[144:145], off offset:576
	v_lshl_add_u64 v[144:145], v[144:145], 0, s[66:67]
	s_waitcnt vmcnt(8)
	v_pk_mul_f32 v[126:127], v[126:127], v[210:211]
	v_pk_mul_f32 v[124:125], v[124:125], v[208:209]
	v_pk_mul_f32 v[122:123], v[122:123], v[214:215]
	v_pk_mul_f32 v[120:121], v[120:121], v[212:213]
	v_pk_mul_f32 v[118:119], v[118:119], v[218:219]
	v_pk_mul_f32 v[116:117], v[116:117], v[216:217]
	v_pk_mul_f32 v[114:115], v[114:115], v[222:223]
	v_pk_mul_f32 v[112:113], v[112:113], v[220:221]
	global_store_dwordx4 v[146:147], v[124:127], off sc0 sc1
	global_store_dwordx4 v[146:147], v[120:123], off offset:64 sc0 sc1
	global_store_dwordx4 v[146:147], v[116:119], off offset:512 sc0 sc1
	global_store_dwordx4 v[146:147], v[112:115], off offset:576 sc0 sc1
	v_lshl_add_u64 v[146:147], v[146:147], 0, s[70:71]
	global_load_dwordx4 v[208:211], v[144:145], off
	global_load_dwordx4 v[212:215], v[144:145], off offset:64
	global_load_dwordx4 v[216:219], v[144:145], off offset:512
	global_load_dwordx4 v[220:223], v[144:145], off offset:576
	v_lshl_add_u64 v[144:145], v[144:145], 0, s[68:69]
	s_waitcnt vmcnt(12)
	v_pk_mul_f32 v[110:111], v[110:111], v[226:227]
	v_pk_mul_f32 v[108:109], v[108:109], v[224:225]
	v_pk_mul_f32 v[106:107], v[106:107], v[230:231]
	v_pk_mul_f32 v[104:105], v[104:105], v[228:229]
	v_pk_mul_f32 v[102:103], v[102:103], v[234:235]
	v_pk_mul_f32 v[100:101], v[100:101], v[232:233]
	v_pk_mul_f32 v[98:99], v[98:99], v[238:239]
	v_pk_mul_f32 v[96:97], v[96:97], v[236:237]
	global_store_dwordx4 v[146:147], v[108:111], off sc0 sc1
	global_store_dwordx4 v[146:147], v[104:107], off offset:64 sc0 sc1
	global_store_dwordx4 v[146:147], v[100:103], off offset:512 sc0 sc1
	global_store_dwordx4 v[146:147], v[96:99], off offset:576 sc0 sc1
	v_lshl_add_u64 v[146:147], v[146:147], 0, s[70:71]
	global_load_dwordx4 v[224:227], v[144:145], off
	global_load_dwordx4 v[228:231], v[144:145], off offset:64
	global_load_dwordx4 v[232:235], v[144:145], off offset:512
	global_load_dwordx4 v[236:239], v[144:145], off offset:576
	v_lshl_add_u64 v[144:145], v[144:145], 0, s[66:67]
	s_waitcnt vmcnt(16)
	v_pk_mul_f32 v[94:95], v[94:95], v[242:243]
	v_pk_mul_f32 v[92:93], v[92:93], v[240:241]
	v_pk_mul_f32 v[90:91], v[90:91], v[246:247]
	v_pk_mul_f32 v[88:89], v[88:89], v[244:245]
	v_pk_mul_f32 v[86:87], v[86:87], v[250:251]
	v_pk_mul_f32 v[84:85], v[84:85], v[248:249]
	v_pk_mul_f32 v[82:83], v[82:83], v[186:187]
	v_pk_mul_f32 v[80:81], v[80:81], v[184:185]
	global_store_dwordx4 v[146:147], v[92:95], off sc0 sc1
	global_store_dwordx4 v[146:147], v[88:91], off offset:64 sc0 sc1
	global_store_dwordx4 v[146:147], v[84:87], off offset:512 sc0 sc1
	global_store_dwordx4 v[146:147], v[80:83], off offset:576 sc0 sc1
	v_lshl_add_u64 v[146:147], v[146:147], 0, s[70:71]
	global_load_dwordx4 v[240:243], v[144:145], off
	global_load_dwordx4 v[244:247], v[144:145], off offset:64
	global_load_dwordx4 v[248:251], v[144:145], off offset:512
	global_load_dwordx4 v[184:187], v[144:145], off offset:576
	v_lshl_add_u64 v[144:145], v[144:145], 0, s[66:67]
	s_waitcnt vmcnt(16)
;     __device__ __forceinline__ void operator()(const Acc& acc, const Unit& u, int wr, int wc, int fr, int fq) const {
;     ...
;                     for (int n = 0; n < 2; ++n) { const int col = u.pn * 256 + bj * 128 + wc * 32 + n * 16 + fq * 4;
;                         const f32x4 ga = *(const f32x4*)(gp + col) * acc[ai][bj][m][n];
;                         if (u.split) { *(f32x4*)(part + ((size_t)(u.k0 >> 8) * MS + (row - MP)) * D + col) = ga;
;                         } else *(f32x4*)(X + (size_t)row * D + col) = *(const f32x4*)(base + col) + ga; } }
	v_pk_mul_f32 v[78:79], v[78:79], v[210:211]
	v_pk_mul_f32 v[76:77], v[76:77], v[208:209]
	v_pk_mul_f32 v[74:75], v[74:75], v[214:215]
	v_pk_mul_f32 v[72:73], v[72:73], v[212:213]
	v_pk_mul_f32 v[70:71], v[70:71], v[218:219]
	v_pk_mul_f32 v[68:69], v[68:69], v[216:217]
	v_pk_mul_f32 v[66:67], v[66:67], v[222:223]
	v_pk_mul_f32 v[64:65], v[64:65], v[220:221]
	global_store_dwordx4 v[146:147], v[76:79], off sc0 sc1
	global_store_dwordx4 v[146:147], v[72:75], off offset:64 sc0 sc1
	global_store_dwordx4 v[146:147], v[68:71], off offset:512 sc0 sc1
	global_store_dwordx4 v[146:147], v[64:67], off offset:576 sc0 sc1
	v_lshl_add_u64 v[146:147], v[146:147], 0, s[98:99]
	global_load_dwordx4 v[208:211], v[144:145], off
	global_load_dwordx4 v[212:215], v[144:145], off offset:64
	global_load_dwordx4 v[216:219], v[144:145], off offset:512
	global_load_dwordx4 v[220:223], v[144:145], off offset:576
	v_lshl_add_u64 v[144:145], v[144:145], 0, s[66:67]
	s_waitcnt vmcnt(16)
	v_pk_mul_f32 v[62:63], v[62:63], v[226:227]
	v_pk_mul_f32 v[60:61], v[60:61], v[224:225]
	v_pk_mul_f32 v[58:59], v[58:59], v[230:231]
	v_pk_mul_f32 v[56:57], v[56:57], v[228:229]
	v_pk_mul_f32 v[54:55], v[54:55], v[234:235]
	v_pk_mul_f32 v[52:53], v[52:53], v[232:233]
	v_pk_mul_f32 v[50:51], v[50:51], v[238:239]
	v_pk_mul_f32 v[48:49], v[48:49], v[236:237]
	global_store_dwordx4 v[146:147], v[60:63], off sc0 sc1
	global_store_dwordx4 v[146:147], v[56:59], off offset:64 sc0 sc1
	global_store_dwordx4 v[146:147], v[52:55], off offset:512 sc0 sc1
	global_store_dwordx4 v[146:147], v[48:51], off offset:576 sc0 sc1
	v_lshl_add_u64 v[146:147], v[146:147], 0, s[70:71]
	global_load_dwordx4 v[224:227], v[144:145], off
	global_load_dwordx4 v[228:231], v[144:145], off offset:64
	global_load_dwordx4 v[232:235], v[144:145], off offset:512
	global_load_dwordx4 v[236:239], v[144:145], off offset:576
	s_waitcnt vmcnt(16)
	v_pk_mul_f32 v[46:47], v[46:47], v[242:243]
	v_pk_mul_f32 v[44:45], v[44:45], v[240:241]
	v_pk_mul_f32 v[42:43], v[42:43], v[246:247]
	v_pk_mul_f32 v[40:41], v[40:41], v[244:245]
	v_pk_mul_f32 v[38:39], v[38:39], v[250:251]
	v_pk_mul_f32 v[36:37], v[36:37], v[248:249]
	v_pk_mul_f32 v[34:35], v[34:35], v[186:187]
	v_pk_mul_f32 v[32:33], v[32:33], v[184:185]
	global_store_dwordx4 v[146:147], v[44:47], off sc0 sc1
	global_store_dwordx4 v[146:147], v[40:43], off offset:64 sc0 sc1
	global_store_dwordx4 v[146:147], v[36:39], off offset:512 sc0 sc1
	global_store_dwordx4 v[146:147], v[32:35], off offset:576 sc0 sc1
	v_lshl_add_u64 v[146:147], v[146:147], 0, s[70:71]
	s_waitcnt vmcnt(12)
	v_pk_mul_f32 v[30:31], v[30:31], v[210:211]
	v_pk_mul_f32 v[28:29], v[28:29], v[208:209]
	v_pk_mul_f32 v[26:27], v[26:27], v[214:215]
	v_pk_mul_f32 v[24:25], v[24:25], v[212:213]
	v_pk_mul_f32 v[22:23], v[22:23], v[218:219]
	v_pk_mul_f32 v[20:21], v[20:21], v[216:217]
	v_pk_mul_f32 v[18:19], v[18:19], v[222:223]
	v_pk_mul_f32 v[16:17], v[16:17], v[220:221]
	global_store_dwordx4 v[146:147], v[28:31], off sc0 sc1
	global_store_dwordx4 v[146:147], v[24:27], off offset:64 sc0 sc1
	global_store_dwordx4 v[146:147], v[20:23], off offset:512 sc0 sc1
	global_store_dwordx4 v[146:147], v[16:19], off offset:576 sc0 sc1
	v_lshl_add_u64 v[146:147], v[146:147], 0, s[70:71]
	s_waitcnt vmcnt(8)
	v_pk_mul_f32 v[14:15], v[14:15], v[226:227]
	v_pk_mul_f32 v[12:13], v[12:13], v[224:225]
	v_pk_mul_f32 v[10:11], v[10:11], v[230:231]
	v_pk_mul_f32 v[8:9], v[8:9], v[228:229]
	v_pk_mul_f32 v[6:7], v[6:7], v[234:235]
	v_pk_mul_f32 v[4:5], v[4:5], v[232:233]
	v_pk_mul_f32 v[2:3], v[2:3], v[238:239]
	v_pk_mul_f32 v[0:1], v[0:1], v[236:237]
	global_store_dwordx4 v[146:147], v[12:15], off sc0 sc1
	global_store_dwordx4 v[146:147], v[8:11], off offset:64 sc0 sc1
	global_store_dwordx4 v[146:147], v[4:7], off offset:512 sc0 sc1
	global_store_dwordx4 v[146:147], v[0:3], off offset:576 sc0 sc1
	s_waitcnt vmcnt(0)
	s_barrier
	v_readlane_b32 s25, v253, 2
	s_nop 3
	s_cmp_eq_u32 s25, 0
	s_cbranch_scc0 .Lepi_dn_noarr
	s_sub_u32 s2, s10, 0x7dffec0
	s_subb_u32 s3, s11, 0
	s_mov_b64 exec, 1
	v_mov_b32_e32 v207, 0
	v_mov_b32_e32 v159, 1
	global_atomic_add v207, v159, s[2:3]
	s_mov_b64 exec, -1
.Lepi_dn_noarr:
.Lepi_dn_done:
	s_and_b64 vcc, exec, s[0:1]
	s_mov_b64 s[0:1], -1
	s_cbranch_vccnz .LBB0_1864
	s_andn2_b64 vcc, exec, s[8:9]
	s_cbranch_vccnz .LBB0_1863
	s_barrier
	s_branch .LBB0_1863

.LBB0_2030:
	s_add_i32 s22, s73, 8
	s_cmp_ge_i32 s22, s79
	s_branch .LBB0_2084
	s_waitcnt vmcnt(0) lgkmcnt(0)
	s_lshl_b32 s0, s29, 6
	v_sub_u32_e32 v0, 0, v150
	v_cmp_eq_u32_e32 vcc, s0, v0
	s_waitcnt vmcnt(0)
	s_barrier
	s_and_saveexec_b64 s[0:1], vcc
	s_cbranch_execz .LBB0_2083
	v_readlane_b32 s3, v253, 8
	s_getreg_b32 s2, hwreg(HW_REG_XCC_ID, 0, 4)
	s_and_b32 s18, s2, 15
	v_mov_b32_e32 v0, s3
	ds_read_b32 v2, v0
	v_readlane_b32 s3, v253, 9
	s_waitcnt lgkmcnt(0)
	v_cmp_ne_u32_e32 vcc, 0, v2
	v_mov_b32_e32 v0, s3
	ds_read_b32 v0, v0
	s_cbranch_vccnz .LBB0_2047
	s_add_u32 s2, s4, 0x1000
	s_addc_u32 s3, s5, 0
	s_add_u32 s6, s4, 0x1100
	s_addc_u32 s7, s5, 0
	s_add_u32 s8, s4, 0x1200
	s_addc_u32 s9, s5, 0
	s_add_u32 s10, s4, 0x1300
	s_addc_u32 s11, s5, 0
	s_mov_b32 s19, 1
	s_branch .LBB0_2035

; #define INP(i) ((const float*)ld_ptr(pb, (i)))
; __global__ void __launch_bounds__(512, 2) hybrid_fwd(Params P) {
;     ...
;         if (l + 1 < DEPTH) norm_rows<false>(nullptr, nullptr, X, INP(9) + (l + 1) * D, (MOD + (size_t)l * NMODROWS * 6144) + (size_t)NMODROWS * 6144, (MOD + (size_t)l * NMODROWS * 6144) + (size_t)NMODROWS * 6144 + 1024, XN, nullptr, gw, NGW, lane, (const float*)(ws + WS_PART), DFF / 256);
;         else norm_rows<true>(nullptr, nullptr, X, INP(33), nullptr, nullptr, nullptr, out, gw, NGW, lane, (const float*)(ws + WS_PART), DFF / 256);
.LBB0_2087:
	v_readlane_b32 s1, v253, 7
	v_readlane_b32 s18, v253, 1
	v_readlane_b32 s0, v253, 0
	v_readlane_b32 s14, v253, 2
	v_mov_b32_e32 v207, s1
	v_mbcnt_lo_u32_b32 v160, -1, 0
	v_mbcnt_hi_u32_b32 v160, -1, v160
	ds_read2_b64 v[0:3], v207 offset0:34 offset1:35
	s_lshl_b32 s0, s0, 3
	s_lshl_b32 s4, s18, 3
	s_add_i32 s6, s0, s14
	s_add_i32 s6, s6, 0x4000
	s_cmp_eq_u32 s96, 3
	s_waitcnt lgkmcnt(0)
	v_readfirstlane_b32 s3, v3
	v_readfirstlane_b32 s2, v2
	v_readfirstlane_b32 s15, v1
	v_readfirstlane_b32 s16, v0
	s_mov_b64 s[0:1], -1
	s_mov_b32 s17, 0x200000
	s_mov_b32 s19, 0x600000
	s_mov_b32 s22, 0x800000
	s_cbranch_scc1 .LBB0_2096
	ds_read_b64 v[0:1], v207 offset:72
	s_cmpk_gt_i32 s6, 0x41ff
	s_waitcnt lgkmcnt(0)
	v_readfirstlane_b32 s0, v1
	v_readfirstlane_b32 s1, v0
	s_cbranch_scc1 .LBB0_2095
	s_mul_i32 s7, s96, 120
	s_add_i32 s7, s7, 120
	s_mov_b64 exec, 1
	v_mov_b32_e32 v100, 0x140
	s_mov_b32 s8, 0

; template <bool FINAL>
; __device__ __forceinline__ void norm_rows(const float* xp, const float* xs, const float* X, const float* g, const float* sh, const float* sc, bf16_t* XN, float* out, int gw, int NGW, int lane, const float* part, int nsplit) {
;     f32x4 vnext[4];
;     if (gw < M) { const float* xr0 = xp ? (gw < MP ? xp + (size_t)gw * D : xs + (size_t)(gw - MP) * D) : X + (size_t)gw * D;
; #pragma unroll
;         for (int j = 0; j < 4; ++j) vnext[j] = *(const f32x4*)(xr0 + 4 * lane + 256 * j); }
.Lnw_n1_ok:
	s_mov_b64 exec, -1
	s_mul_i32 s74, s96, 0xc6000
	s_lshl_b64 s[8:9], s[74:75], 2
	s_add_u32 s8, s2, s8
	s_addc_u32 s9, s3, s9
	s_add_u32 s10, s2, 0x7e00000
	s_addc_u32 s11, s3, 0
	s_lshl_b32 s74, s96, 10
	s_lshl_b64 s[12:13], s[74:75], 2
	s_add_u32 s12, s1, s12
	s_addc_u32 s13, s0, s13
	s_ashr_i32 s7, s6, 31
	s_lshl_b64 s[0:1], s[6:7], 12
	v_lshlrev_b32_e32 v0, 2, v160
	s_add_u32 s0, s10, s0
	v_ashrrev_i32_e32 v1, 31, v0
	s_addc_u32 s1, s11, s1
	v_lshlrev_b64 v[2:3], 2, v[0:1]
	v_lshl_add_u64 v[4:5], s[0:1], 0, v[2:3]
	global_load_dwordx4 v[24:27], v[4:5], off
	global_load_dwordx4 v[20:23], v[4:5], off offset:1024
	global_load_dwordx4 v[16:19], v[4:5], off offset:2048
	global_load_dwordx4 v[28:31], v[4:5], off offset:3072
	v_lshl_add_u64 v[4:5], s[2:3], 0, v[2:3]
	s_mov_b64 s[0:1], 0x13c00000
	v_lshl_add_u64 v[184:185], v[4:5], 0, s[0:1]
	v_lshl_add_u64 v[4:5], s[12:13], 0, v[2:3]
	s_mov_b64 s[0:1], 0x1000
	v_lshl_add_u64 v[186:187], s[10:11], 0, v[2:3]
	v_lshl_add_u64 v[188:189], v[4:5], 0, s[0:1]
	v_lshl_add_u64 v[2:3], s[8:9], 0, v[2:3]
	s_mov_b64 s[0:1], 0xb19000
	v_lshl_add_u64 v[190:191], v[2:3], 0, s[0:1]
	s_mov_b64 s[0:1], 0xb18000
	v_lshl_add_u64 v[192:193], v[2:3], 0, s[0:1]
	s_lshl_b64 s[0:1], s[6:7], 11
	s_add_u32 s0, s2, s0
	s_addc_u32 s1, s3, s1
	v_lshl_add_u64 v[0:1], v[0:1], 1, s[0:1]
	s_mov_b64 s[0:1], 0xc000000
	s_ashr_i32 s5, s4, 31
	v_lshl_add_u64 v[194:195], v[0:1], 0, s[0:1]
	s_lshl_b64 s[8:9], s[4:5], 11
	s_mov_b32 s0, s6
	s_branch .LBB0_2091

; template <bool FINAL>
; __device__ __forceinline__ void norm_rows(const float* xp, const float* xs, const float* X, const float* g, const float* sh, const float* sc, bf16_t* XN, float* out, int gw, int NGW, int lane, const float* part, int nsplit) {
;     ...
;         if (nsplit > 0 && row >= MP) {
;             for (int sp = 0; sp < nsplit; ++sp) { const float* pr = part + ((size_t)sp * MS + (row - MP)) * D + 4 * lane;
; #pragma unroll
;                 for (int j = 0; j < 4; ++j) v[j] += *(const f32x4*)(pr + 256 * j); }
; #pragma unroll
;             for (int j = 0; j < 4; ++j) *(f32x4*)((float*)X + (size_t)row * D + 4 * lane + 256 * j) = v[j]; }
.LBB0_2093:
	s_add_i32 s74, s0, 0xffffc000
	s_cmpk_lt_i32 s0, 0x4000
	s_cbranch_scc1 .LBB0_2090
	s_lshl_b64 s[20:21], s[74:75], 12
	v_lshl_add_u64 v[196:197], v[184:185], 0, s[20:21]
	global_load_dwordx4 v[40:43], v[196:197], off sc0 sc1
	global_load_dwordx4 v[44:47], v[196:197], off offset:1024 sc0 sc1
	global_load_dwordx4 v[36:39], v[196:197], off offset:2048 sc0 sc1
	global_load_dwordx4 v[32:35], v[196:197], off offset:3072 sc0 sc1
	v_add_co_u32_e32 v48, vcc, s17, v196
	s_mov_b32 s1, 0x400000
	s_nop 0
	v_addc_co_u32_e32 v49, vcc, 0, v197, vcc
	v_add_co_u32_e32 v64, vcc, s1, v196
	s_mov_b32 s1, 0xa00000
	s_nop 0
	v_addc_co_u32_e32 v65, vcc, 0, v197, vcc
	v_add_co_u32_e32 v80, vcc, s19, v196
	global_load_dwordx4 v[60:63], v[48:49], off sc0 sc1
	global_load_dwordx4 v[56:59], v[48:49], off offset:1024 sc0 sc1
	global_load_dwordx4 v[52:55], v[48:49], off offset:2048 sc0 sc1
	s_nop 0
	global_load_dwordx4 v[48:51], v[48:49], off offset:3072 sc0 sc1
	v_addc_co_u32_e32 v81, vcc, 0, v197, vcc
	v_add_co_u32_e32 v96, vcc, s22, v196
	global_load_dwordx4 v[76:79], v[64:65], off sc0 sc1
	global_load_dwordx4 v[72:75], v[64:65], off offset:1024 sc0 sc1
	global_load_dwordx4 v[68:71], v[64:65], off offset:2048 sc0 sc1
	s_nop 0
	global_load_dwordx4 v[64:67], v[64:65], off offset:3072 sc0 sc1
	v_addc_co_u32_e32 v97, vcc, 0, v197, vcc
	v_add_co_u32_e32 v112, vcc, s1, v196
	s_mov_b32 s1, 0xc00000
	s_nop 0
	v_addc_co_u32_e32 v113, vcc, 0, v197, vcc
	v_add_co_u32_e32 v128, vcc, s1, v196
	s_mov_b32 s1, 0xe00000
	s_nop 0
	v_addc_co_u32_e32 v129, vcc, 0, v197, vcc
	v_add_co_u32_e32 v144, vcc, s1, v196
	global_load_dwordx4 v[92:95], v[80:81], off sc0 sc1
	global_load_dwordx4 v[88:91], v[80:81], off offset:1024 sc0 sc1
	global_load_dwordx4 v[84:87], v[80:81], off offset:2048 sc0 sc1
	s_nop 0
	global_load_dwordx4 v[80:83], v[80:81], off offset:3072 sc0 sc1
	v_addc_co_u32_e32 v145, vcc, 0, v197, vcc
	s_mov_b32 s1, 0x1000000
	global_load_dwordx4 v[108:111], v[96:97], off sc0 sc1
	global_load_dwordx4 v[104:107], v[96:97], off offset:1024 sc0 sc1
	global_load_dwordx4 v[100:103], v[96:97], off offset:2048 sc0 sc1
	s_nop 0
	global_load_dwordx4 v[96:99], v[96:97], off offset:3072 sc0 sc1
	v_add_co_u32_e32 v220, vcc, s1, v196
	global_load_dwordx4 v[124:127], v[112:113], off sc0 sc1
	global_load_dwordx4 v[120:123], v[112:113], off offset:1024 sc0 sc1
	global_load_dwordx4 v[116:119], v[112:113], off offset:2048 sc0 sc1
	s_nop 0
	global_load_dwordx4 v[112:115], v[112:113], off offset:3072 sc0 sc1
	v_addc_co_u32_e32 v221, vcc, 0, v197, vcc
	s_mov_b32 s1, 0x1200000
	global_load_dwordx4 v[140:143], v[128:129], off sc0 sc1
	global_load_dwordx4 v[136:139], v[128:129], off offset:1024 sc0 sc1
	global_load_dwordx4 v[132:135], v[128:129], off offset:2048 sc0 sc1
	s_nop 0
	global_load_dwordx4 v[128:131], v[128:129], off offset:3072 sc0 sc1
	v_add_co_u32_e32 v236, vcc, s1, v196
	global_load_dwordx4 v[156:159], v[144:145], off sc0 sc1
	global_load_dwordx4 v[152:155], v[144:145], off offset:1024 sc0 sc1
	global_load_dwordx4 v[148:151], v[144:145], off offset:2048 sc0 sc1
	s_nop 0
	global_load_dwordx4 v[144:147], v[144:145], off offset:3072 sc0 sc1
	v_addc_co_u32_e32 v237, vcc, 0, v197, vcc
	s_mov_b32 s1, 0x1400000
	global_load_dwordx4 v[208:211], v[220:221], off sc0 sc1
	global_load_dwordx4 v[212:215], v[220:221], off offset:1024 sc0 sc1
	global_load_dwordx4 v[216:219], v[220:221], off offset:2048 sc0 sc1
	s_nop 0
	global_load_dwordx4 v[220:223], v[220:221], off offset:3072 sc0 sc1
	s_nop 0
	global_load_dwordx4 v[224:227], v[236:237], off sc0 sc1
	global_load_dwordx4 v[228:231], v[236:237], off offset:1024 sc0 sc1
	global_load_dwordx4 v[232:235], v[236:237], off offset:2048 sc0 sc1
	s_nop 0
	global_load_dwordx4 v[236:239], v[236:237], off offset:3072 sc0 sc1
	s_waitcnt vmcnt(39)
	v_pk_add_f32 v[26:27], v[26:27], v[42:43]
	s_waitcnt vmcnt(38)
	v_pk_add_f32 v[42:43], v[22:23], v[46:47]
	v_add_co_u32_e32 v46, vcc, s1, v196
	v_pk_add_f32 v[24:25], v[24:25], v[40:41]
	s_nop 0
	v_addc_co_u32_e32 v47, vcc, 0, v197, vcc
	v_pk_add_f32 v[44:45], v[20:21], v[44:45]
	global_load_dwordx4 v[20:23], v[46:47], off sc0 sc1
	s_waitcnt vmcnt(38)
	v_pk_add_f32 v[196:197], v[18:19], v[38:39]
	global_load_dwordx4 v[38:41], v[46:47], off offset:1024 sc0 sc1
	v_pk_add_f32 v[240:241], v[16:17], v[36:37]
	global_load_dwordx4 v[16:19], v[46:47], off offset:2048 sc0 sc1
	s_waitcnt vmcnt(39)
	v_pk_add_f32 v[30:31], v[30:31], v[34:35]
	global_load_dwordx4 v[34:37], v[46:47], off offset:3072 sc0 sc1
	v_pk_add_f32 v[28:29], v[28:29], v[32:33]
	s_waitcnt vmcnt(39)
	v_pk_add_f32 v[26:27], v[26:27], v[62:63]
	v_pk_add_f32 v[24:25], v[24:25], v[60:61]
	s_waitcnt vmcnt(38)
; template <bool FINAL>
; __device__ __forceinline__ void norm_rows(const float* xp, const float* xs, const float* X, const float* g, const float* sh, const float* sc, bf16_t* XN, float* out, int gw, int NGW, int lane, const float* part, int nsplit) {
;     ...
;             for (int sp = 0; sp < nsplit; ++sp) { const float* pr = part + ((size_t)sp * MS + (row - MP)) * D + 4 * lane;
; #pragma unroll
;                 for (int j = 0; j < 4; ++j) v[j] += *(const f32x4*)(pr + 256 * j); }
; #pragma unroll
;             for (int j = 0; j < 4; ++j) *(f32x4*)((float*)X + (size_t)row * D + 4 * lane + 256 * j) = v[j]; }
	v_pk_add_f32 v[32:33], v[44:45], v[56:57]
	v_pk_add_f32 v[42:43], v[42:43], v[58:59]
	s_waitcnt vmcnt(37)
	v_pk_add_f32 v[44:45], v[240:241], v[52:53]
	v_pk_add_f32 v[46:47], v[196:197], v[54:55]
	s_waitcnt vmcnt(36)
	v_pk_add_f32 v[28:29], v[28:29], v[48:49]
	v_pk_add_f32 v[30:31], v[30:31], v[50:51]
	s_waitcnt vmcnt(35)
	v_pk_add_f32 v[26:27], v[26:27], v[78:79]
	v_pk_add_f32 v[24:25], v[24:25], v[76:77]
	s_waitcnt vmcnt(34)
	v_pk_add_f32 v[42:43], v[42:43], v[74:75]
	v_pk_add_f32 v[32:33], v[32:33], v[72:73]
	s_waitcnt vmcnt(33)
	v_pk_add_f32 v[46:47], v[46:47], v[70:71]
	v_pk_add_f32 v[44:45], v[44:45], v[68:69]
	s_waitcnt vmcnt(32)
	v_pk_add_f32 v[30:31], v[30:31], v[66:67]
	v_pk_add_f32 v[28:29], v[28:29], v[64:65]
	s_mov_b32 s1, s75
	s_waitcnt vmcnt(31)
	v_pk_add_f32 v[26:27], v[26:27], v[94:95]
	v_pk_add_f32 v[24:25], v[24:25], v[92:93]
	s_waitcnt vmcnt(30)
	v_pk_add_f32 v[42:43], v[42:43], v[90:91]
	v_pk_add_f32 v[32:33], v[32:33], v[88:89]
	s_waitcnt vmcnt(29)
	v_pk_add_f32 v[46:47], v[46:47], v[86:87]
	v_pk_add_f32 v[44:45], v[44:45], v[84:85]
	s_waitcnt vmcnt(28)
	v_pk_add_f32 v[30:31], v[30:31], v[82:83]
	v_pk_add_f32 v[28:29], v[28:29], v[80:81]
	s_waitcnt vmcnt(27)
	v_pk_add_f32 v[26:27], v[26:27], v[110:111]
	v_pk_add_f32 v[24:25], v[24:25], v[108:109]
	s_waitcnt vmcnt(26)
	v_pk_add_f32 v[42:43], v[42:43], v[106:107]
	v_pk_add_f32 v[32:33], v[32:33], v[104:105]
	s_waitcnt vmcnt(25)
	v_pk_add_f32 v[46:47], v[46:47], v[102:103]
	v_pk_add_f32 v[44:45], v[44:45], v[100:101]
	s_waitcnt vmcnt(24)
	v_pk_add_f32 v[30:31], v[30:31], v[98:99]
	v_pk_add_f32 v[28:29], v[28:29], v[96:97]
	s_waitcnt vmcnt(23)
	v_pk_add_f32 v[26:27], v[26:27], v[126:127]
	v_pk_add_f32 v[24:25], v[24:25], v[124:125]
	s_waitcnt vmcnt(22)
	v_pk_add_f32 v[42:43], v[42:43], v[122:123]
	v_pk_add_f32 v[32:33], v[32:33], v[120:121]
	s_waitcnt vmcnt(21)
	v_pk_add_f32 v[46:47], v[46:47], v[118:119]
	v_pk_add_f32 v[44:45], v[44:45], v[116:117]
	s_waitcnt vmcnt(20)
	v_pk_add_f32 v[30:31], v[30:31], v[114:115]
	v_pk_add_f32 v[28:29], v[28:29], v[112:113]
	s_waitcnt vmcnt(19)
	v_pk_add_f32 v[26:27], v[26:27], v[142:143]
	v_pk_add_f32 v[24:25], v[24:25], v[140:141]
	s_waitcnt vmcnt(18)
	v_pk_add_f32 v[42:43], v[42:43], v[138:139]
	v_pk_add_f32 v[32:33], v[32:33], v[136:137]
	s_waitcnt vmcnt(17)
	v_pk_add_f32 v[46:47], v[46:47], v[134:135]
	v_pk_add_f32 v[44:45], v[44:45], v[132:133]
	s_waitcnt vmcnt(16)
	v_pk_add_f32 v[30:31], v[30:31], v[130:131]
	v_pk_add_f32 v[28:29], v[28:29], v[128:129]
	s_waitcnt vmcnt(15)
	v_pk_add_f32 v[26:27], v[26:27], v[158:159]
	v_pk_add_f32 v[24:25], v[24:25], v[156:157]
	s_waitcnt vmcnt(14)
	v_pk_add_f32 v[42:43], v[42:43], v[154:155]
	v_pk_add_f32 v[32:33], v[32:33], v[152:153]
	s_waitcnt vmcnt(13)
	v_pk_add_f32 v[46:47], v[46:47], v[150:151]
	v_pk_add_f32 v[44:45], v[44:45], v[148:149]
	s_waitcnt vmcnt(12)
	v_pk_add_f32 v[30:31], v[30:31], v[146:147]
	v_pk_add_f32 v[28:29], v[28:29], v[144:145]
	s_waitcnt vmcnt(11)
	v_pk_add_f32 v[26:27], v[26:27], v[210:211]
	v_pk_add_f32 v[24:25], v[24:25], v[208:209]
	s_waitcnt vmcnt(10)
	v_pk_add_f32 v[42:43], v[42:43], v[214:215]
	v_pk_add_f32 v[32:33], v[32:33], v[212:213]
	s_waitcnt vmcnt(9)
	v_pk_add_f32 v[46:47], v[46:47], v[218:219]
	v_pk_add_f32 v[44:45], v[44:45], v[216:217]
	s_waitcnt vmcnt(8)
	v_pk_add_f32 v[30:31], v[30:31], v[222:223]
	v_pk_add_f32 v[28:29], v[28:29], v[220:221]
	s_waitcnt vmcnt(7)
	v_pk_add_f32 v[26:27], v[26:27], v[226:227]
	v_pk_add_f32 v[24:25], v[24:25], v[224:225]
	s_waitcnt vmcnt(6)
	v_pk_add_f32 v[42:43], v[42:43], v[230:231]
	v_pk_add_f32 v[32:33], v[32:33], v[228:229]
	s_waitcnt vmcnt(5)
	v_pk_add_f32 v[46:47], v[46:47], v[234:235]
	v_pk_add_f32 v[44:45], v[44:45], v[232:233]
	s_waitcnt vmcnt(4)
	v_pk_add_f32 v[30:31], v[30:31], v[238:239]
	v_pk_add_f32 v[28:29], v[28:29], v[236:237]
	s_lshl_b64 s[20:21], s[0:1], 12
	s_waitcnt vmcnt(3)
	v_pk_add_f32 v[26:27], v[26:27], v[22:23]
	v_pk_add_f32 v[24:25], v[24:25], v[20:21]
	s_waitcnt vmcnt(2)
	v_pk_add_f32 v[22:23], v[42:43], v[40:41]
	v_pk_add_f32 v[20:21], v[32:33], v[38:39]
	s_waitcnt vmcnt(1)
	v_pk_add_f32 v[18:19], v[46:47], v[18:19]
	v_pk_add_f32 v[16:17], v[44:45], v[16:17]
	s_waitcnt vmcnt(0)
	v_pk_add_f32 v[30:31], v[30:31], v[36:37]
	v_pk_add_f32 v[28:29], v[28:29], v[34:35]
	v_lshl_add_u64 v[32:33], v[186:187], 0, s[20:21]
	global_store_dwordx4 v[32:33], v[24:27], off
	global_store_dwordx4 v[32:33], v[20:23], off offset:1024
	global_store_dwordx4 v[32:33], v[16:19], off offset:2048
	global_store_dwordx4 v[32:33], v[28:31], off offset:3072
	s_branch .LBB0_2090

; #define INP(i) ((const float*)ld_ptr(pb, (i)))
; __global__ void __launch_bounds__(512, 2) hybrid_fwd(Params P) {
;     ...
;         else norm_rows<true>(nullptr, nullptr, X, INP(33), nullptr, nullptr, nullptr, out, gw, NGW, lane, (const float*)(ws + WS_PART), DFF / 256);
.LBB0_2096:
	s_andn2_b64 vcc, exec, s[0:1]
	s_cbranch_vccnz .LBB0_2104
	ds_read_b64 v[0:1], v207 offset:264
	s_cmpk_gt_i32 s6, 0x41ff
	s_waitcnt lgkmcnt(0)
	v_readfirstlane_b32 s1, v1
	v_readfirstlane_b32 s0, v0
	s_cbranch_scc1 .LBB0_2104
	s_mul_i32 s7, s96, 120
	s_add_i32 s7, s7, 120
	s_mov_b64 exec, 1
	v_mov_b32_e32 v100, 0x140
	s_mov_b32 s8, 0

; template <bool FINAL>
; __device__ __forceinline__ void norm_rows(const float* xp, const float* xs, const float* X, const float* g, const float* sh, const float* sc, bf16_t* XN, float* out, int gw, int NGW, int lane, const float* part, int nsplit) {
;     f32x4 vnext[4];
;     if (gw < M) { const float* xr0 = xp ? (gw < MP ? xp + (size_t)gw * D : xs + (size_t)(gw - MP) * D) : X + (size_t)gw * D;
; #pragma unroll
;         for (int j = 0; j < 4; ++j) vnext[j] = *(const f32x4*)(xr0 + 4 * lane + 256 * j); }
.Lnw_nf_ok:
	s_mov_b64 exec, -1
	s_add_u32 s8, s2, 0x7e00000
	s_addc_u32 s9, s3, 0
	s_ashr_i32 s7, s6, 31
	s_lshl_b64 s[10:11], s[6:7], 12
	v_lshlrev_b32_e32 v0, 2, v160
	s_add_u32 s12, s8, s10
	v_ashrrev_i32_e32 v1, 31, v0
	s_addc_u32 s13, s9, s11
	v_lshlrev_b64 v[4:5], 2, v[0:1]
	v_lshl_add_u64 v[0:1], s[12:13], 0, v[4:5]
	global_load_dwordx4 v[28:31], v[0:1], off
	global_load_dwordx4 v[24:27], v[0:1], off offset:1024
	global_load_dwordx4 v[20:23], v[0:1], off offset:2048
	s_nop 0
	global_load_dwordx4 v[0:3], v[0:1], off offset:3072
	s_add_i32 s74, s6, 0xffffc000
	v_lshl_add_u64 v[68:69], s[0:1], 0, v[4:5]
	s_add_u32 s0, s16, s10
	s_addc_u32 s1, s15, s11
	v_lshl_add_u64 v[64:65], s[8:9], 0, v[4:5]
	v_lshl_add_u64 v[6:7], s[2:3], 0, v[4:5]
	s_mov_b64 s[8:9], 0x13c00000
	v_lshl_add_u64 v[4:5], s[0:1], 0, v[4:5]
	s_mov_b64 s[0:1], 0xc00
	s_ashr_i32 s5, s4, 31
	v_lshl_add_u64 v[66:67], v[6:7], 0, s[8:9]
	v_lshl_add_u64 v[70:71], v[4:5], 0, s[0:1]
	s_lshl_b64 s[6:7], s[4:5], 12
	s_branch .LBB0_2100

; template <bool FINAL>
; __device__ __forceinline__ void norm_rows(const float* xp, const float* xs, const float* X, const float* g, const float* sh, const float* sc, bf16_t* XN, float* out, int gw, int NGW, int lane, const float* part, int nsplit) {
;     ...
;         if (nsplit > 0 && row >= MP) {
;             for (int sp = 0; sp < nsplit; ++sp) { const float* pr = part + ((size_t)sp * MS + (row - MP)) * D + 4 * lane;
; #pragma unroll
;                 for (int j = 0; j < 4; ++j) v[j] += *(const f32x4*)(pr + 256 * j); }
; #pragma unroll
;             for (int j = 0; j < 4; ++j) *(f32x4*)((float*)X + (size_t)row * D + 4 * lane + 256 * j) = v[j]; }
.LBB0_2102:
	s_add_i32 s0, s74, 0x4000
	s_cmpk_lt_i32 s0, 0x4000
	s_cbranch_scc1 .LBB0_2099
	s_lshl_b64 s[10:11], s[74:75], 12
	v_lshl_add_u64 v[72:73], v[66:67], 0, s[10:11]
	global_load_dwordx4 v[40:43], v[72:73], off sc0 sc1
	global_load_dwordx4 v[44:47], v[72:73], off offset:1024 sc0 sc1
	global_load_dwordx4 v[36:39], v[72:73], off offset:2048 sc0 sc1
	global_load_dwordx4 v[32:35], v[72:73], off offset:3072 sc0 sc1
	v_add_co_u32_e32 v48, vcc, s17, v72
	s_mov_b32 s1, 0x400000
	s_nop 0
	v_addc_co_u32_e32 v49, vcc, 0, v73, vcc
	v_add_co_u32_e32 v86, vcc, s1, v72
	s_mov_b32 s1, 0xa00000
	s_nop 0
	v_addc_co_u32_e32 v87, vcc, 0, v73, vcc
	v_add_co_u32_e32 v102, vcc, s19, v72
	global_load_dwordx4 v[60:63], v[48:49], off sc0 sc1
	global_load_dwordx4 v[56:59], v[48:49], off offset:1024 sc0 sc1
	global_load_dwordx4 v[52:55], v[48:49], off offset:2048 sc0 sc1
	s_nop 0
	global_load_dwordx4 v[48:51], v[48:49], off offset:3072 sc0 sc1
	v_addc_co_u32_e32 v103, vcc, 0, v73, vcc
	v_add_co_u32_e32 v118, vcc, s22, v72
	global_load_dwordx4 v[74:77], v[86:87], off sc0 sc1
	global_load_dwordx4 v[78:81], v[86:87], off offset:1024 sc0 sc1
	global_load_dwordx4 v[82:85], v[86:87], off offset:2048 sc0 sc1
	s_nop 0
	global_load_dwordx4 v[86:89], v[86:87], off offset:3072 sc0 sc1
	v_addc_co_u32_e32 v119, vcc, 0, v73, vcc
	v_add_co_u32_e32 v134, vcc, s1, v72
	s_mov_b32 s1, 0xc00000
	s_nop 0
	v_addc_co_u32_e32 v135, vcc, 0, v73, vcc
	v_add_co_u32_e32 v150, vcc, s1, v72
	s_mov_b32 s1, 0xe00000
	s_nop 0
	v_addc_co_u32_e32 v151, vcc, 0, v73, vcc
	v_add_co_u32_e32 v158, vcc, s1, v72
	global_load_dwordx4 v[90:93], v[102:103], off sc0 sc1
	global_load_dwordx4 v[94:97], v[102:103], off offset:1024 sc0 sc1
	global_load_dwordx4 v[98:101], v[102:103], off offset:2048 sc0 sc1
	s_nop 0
	global_load_dwordx4 v[102:105], v[102:103], off offset:3072 sc0 sc1
	v_addc_co_u32_e32 v159, vcc, 0, v73, vcc
	s_mov_b32 s1, 0x1000000
	global_load_dwordx4 v[106:109], v[118:119], off sc0 sc1
	global_load_dwordx4 v[110:113], v[118:119], off offset:1024 sc0 sc1
	global_load_dwordx4 v[114:117], v[118:119], off offset:2048 sc0 sc1
	s_nop 0
	global_load_dwordx4 v[118:121], v[118:119], off offset:3072 sc0 sc1
	v_add_co_u32_e32 v196, vcc, s1, v72
	global_load_dwordx4 v[122:125], v[134:135], off sc0 sc1
	global_load_dwordx4 v[126:129], v[134:135], off offset:1024 sc0 sc1
	global_load_dwordx4 v[130:133], v[134:135], off offset:2048 sc0 sc1
	s_nop 0
	global_load_dwordx4 v[134:137], v[134:135], off offset:3072 sc0 sc1
	v_addc_co_u32_e32 v197, vcc, 0, v73, vcc
	s_mov_b32 s1, 0x1200000
	global_load_dwordx4 v[138:141], v[150:151], off sc0 sc1
	global_load_dwordx4 v[142:145], v[150:151], off offset:1024 sc0 sc1
	global_load_dwordx4 v[146:149], v[150:151], off offset:2048 sc0 sc1
	s_nop 0
	global_load_dwordx4 v[150:153], v[150:151], off offset:3072 sc0 sc1
	s_nop 0
	global_load_dwordx4 v[154:157], v[158:159], off sc0 sc1
	global_load_dwordx4 v[184:187], v[158:159], off offset:1024 sc0 sc1
	global_load_dwordx4 v[188:191], v[158:159], off offset:2048 sc0 sc1
	global_load_dwordx4 v[192:195], v[158:159], off offset:3072 sc0 sc1
	v_add_co_u32_e32 v158, vcc, s1, v72
	s_mov_b32 s1, 0x1400000
	s_nop 0
	v_addc_co_u32_e32 v159, vcc, 0, v73, vcc
	global_load_dwordx4 v[208:211], v[196:197], off sc0 sc1
	global_load_dwordx4 v[212:215], v[196:197], off offset:1024 sc0 sc1
	global_load_dwordx4 v[216:219], v[196:197], off offset:2048 sc0 sc1
	global_load_dwordx4 v[220:223], v[196:197], off offset:3072 sc0 sc1
	global_load_dwordx4 v[224:227], v[158:159], off sc0 sc1
	global_load_dwordx4 v[228:231], v[158:159], off offset:1024 sc0 sc1
	global_load_dwordx4 v[232:235], v[158:159], off offset:2048 sc0 sc1
	global_load_dwordx4 v[236:239], v[158:159], off offset:3072 sc0 sc1
	s_waitcnt vmcnt(39)
	v_pk_add_f32 v[30:31], v[30:31], v[42:43]
	s_waitcnt vmcnt(38)
	v_pk_add_f32 v[42:43], v[26:27], v[46:47]
	v_add_co_u32_e32 v46, vcc, s1, v72
	v_pk_add_f32 v[28:29], v[28:29], v[40:41]
	s_nop 0
	v_addc_co_u32_e32 v47, vcc, 0, v73, vcc
	v_pk_add_f32 v[44:45], v[24:25], v[44:45]
	global_load_dwordx4 v[24:27], v[46:47], off sc0 sc1
	s_waitcnt vmcnt(38)
	v_pk_add_f32 v[72:73], v[22:23], v[38:39]
	global_load_dwordx4 v[38:41], v[46:47], off offset:1024 sc0 sc1
	v_pk_add_f32 v[158:159], v[20:21], v[36:37]
	global_load_dwordx4 v[20:23], v[46:47], off offset:2048 sc0 sc1
	s_waitcnt vmcnt(39)
	v_pk_add_f32 v[2:3], v[2:3], v[34:35]
	global_load_dwordx4 v[34:37], v[46:47], off offset:3072 sc0 sc1
	v_pk_add_f32 v[0:1], v[0:1], v[32:33]
	s_waitcnt vmcnt(39)
; template <bool FINAL>
; __device__ __forceinline__ void norm_rows(const float* xp, const float* xs, const float* X, const float* g, const float* sh, const float* sc, bf16_t* XN, float* out, int gw, int NGW, int lane, const float* part, int nsplit) {
;     ...
;             for (int sp = 0; sp < nsplit; ++sp) { const float* pr = part + ((size_t)sp * MS + (row - MP)) * D + 4 * lane;
; #pragma unroll
;                 for (int j = 0; j < 4; ++j) v[j] += *(const f32x4*)(pr + 256 * j); }
; #pragma unroll
;             for (int j = 0; j < 4; ++j) *(f32x4*)((float*)X + (size_t)row * D + 4 * lane + 256 * j) = v[j]; }
	v_pk_add_f32 v[30:31], v[30:31], v[62:63]
	v_pk_add_f32 v[28:29], v[28:29], v[60:61]
	s_waitcnt vmcnt(38)
	v_pk_add_f32 v[32:33], v[44:45], v[56:57]
	v_pk_add_f32 v[42:43], v[42:43], v[58:59]
	s_waitcnt vmcnt(37)
	v_pk_add_f32 v[44:45], v[158:159], v[52:53]
	v_pk_add_f32 v[46:47], v[72:73], v[54:55]
	s_waitcnt vmcnt(36)
	v_pk_add_f32 v[0:1], v[0:1], v[48:49]
	v_pk_add_f32 v[2:3], v[2:3], v[50:51]
	s_waitcnt vmcnt(35)
	v_pk_add_f32 v[30:31], v[30:31], v[76:77]
	v_pk_add_f32 v[28:29], v[28:29], v[74:75]
	s_waitcnt vmcnt(34)
	v_pk_add_f32 v[42:43], v[42:43], v[80:81]
	v_pk_add_f32 v[32:33], v[32:33], v[78:79]
	s_waitcnt vmcnt(33)
	v_pk_add_f32 v[46:47], v[46:47], v[84:85]
	v_pk_add_f32 v[44:45], v[44:45], v[82:83]
	s_waitcnt vmcnt(32)
	v_pk_add_f32 v[2:3], v[2:3], v[88:89]
	v_pk_add_f32 v[0:1], v[0:1], v[86:87]
	s_mov_b32 s1, s75
	s_waitcnt vmcnt(31)
	v_pk_add_f32 v[30:31], v[30:31], v[92:93]
	v_pk_add_f32 v[28:29], v[28:29], v[90:91]
	s_waitcnt vmcnt(30)
	v_pk_add_f32 v[42:43], v[42:43], v[96:97]
	v_pk_add_f32 v[32:33], v[32:33], v[94:95]
	s_waitcnt vmcnt(29)
	v_pk_add_f32 v[46:47], v[46:47], v[100:101]
	v_pk_add_f32 v[44:45], v[44:45], v[98:99]
	s_waitcnt vmcnt(28)
	v_pk_add_f32 v[2:3], v[2:3], v[104:105]
	v_pk_add_f32 v[0:1], v[0:1], v[102:103]
	s_waitcnt vmcnt(27)
	v_pk_add_f32 v[30:31], v[30:31], v[108:109]
	v_pk_add_f32 v[28:29], v[28:29], v[106:107]
	s_waitcnt vmcnt(26)
	v_pk_add_f32 v[42:43], v[42:43], v[112:113]
	v_pk_add_f32 v[32:33], v[32:33], v[110:111]
	s_waitcnt vmcnt(25)
	v_pk_add_f32 v[46:47], v[46:47], v[116:117]
	v_pk_add_f32 v[44:45], v[44:45], v[114:115]
	s_waitcnt vmcnt(24)
	v_pk_add_f32 v[2:3], v[2:3], v[120:121]
	v_pk_add_f32 v[0:1], v[0:1], v[118:119]
	s_waitcnt vmcnt(23)
	v_pk_add_f32 v[30:31], v[30:31], v[124:125]
	v_pk_add_f32 v[28:29], v[28:29], v[122:123]
	s_waitcnt vmcnt(22)
	v_pk_add_f32 v[42:43], v[42:43], v[128:129]
	v_pk_add_f32 v[32:33], v[32:33], v[126:127]
	s_waitcnt vmcnt(21)
	v_pk_add_f32 v[46:47], v[46:47], v[132:133]
	v_pk_add_f32 v[44:45], v[44:45], v[130:131]
	s_waitcnt vmcnt(20)
	v_pk_add_f32 v[2:3], v[2:3], v[136:137]
	v_pk_add_f32 v[0:1], v[0:1], v[134:135]
	s_waitcnt vmcnt(19)
	v_pk_add_f32 v[30:31], v[30:31], v[140:141]
	v_pk_add_f32 v[28:29], v[28:29], v[138:139]
	s_waitcnt vmcnt(18)
	v_pk_add_f32 v[42:43], v[42:43], v[144:145]
	v_pk_add_f32 v[32:33], v[32:33], v[142:143]
	s_waitcnt vmcnt(17)
	v_pk_add_f32 v[46:47], v[46:47], v[148:149]
	v_pk_add_f32 v[44:45], v[44:45], v[146:147]
	s_waitcnt vmcnt(16)
	v_pk_add_f32 v[2:3], v[2:3], v[152:153]
	v_pk_add_f32 v[0:1], v[0:1], v[150:151]
	s_waitcnt vmcnt(15)
	v_pk_add_f32 v[30:31], v[30:31], v[156:157]
	v_pk_add_f32 v[28:29], v[28:29], v[154:155]
	s_waitcnt vmcnt(14)
	v_pk_add_f32 v[42:43], v[42:43], v[186:187]
	v_pk_add_f32 v[32:33], v[32:33], v[184:185]
	s_waitcnt vmcnt(13)
	v_pk_add_f32 v[46:47], v[46:47], v[190:191]
	v_pk_add_f32 v[44:45], v[44:45], v[188:189]
	s_waitcnt vmcnt(12)
	v_pk_add_f32 v[2:3], v[2:3], v[194:195]
	v_pk_add_f32 v[0:1], v[0:1], v[192:193]
	s_waitcnt vmcnt(11)
	v_pk_add_f32 v[30:31], v[30:31], v[210:211]
	v_pk_add_f32 v[28:29], v[28:29], v[208:209]
	s_waitcnt vmcnt(10)
	v_pk_add_f32 v[42:43], v[42:43], v[214:215]
	v_pk_add_f32 v[32:33], v[32:33], v[212:213]
	s_waitcnt vmcnt(9)
	v_pk_add_f32 v[46:47], v[46:47], v[218:219]
	v_pk_add_f32 v[44:45], v[44:45], v[216:217]
	s_waitcnt vmcnt(8)
	v_pk_add_f32 v[2:3], v[2:3], v[222:223]
	v_pk_add_f32 v[0:1], v[0:1], v[220:221]
	s_waitcnt vmcnt(7)
	v_pk_add_f32 v[30:31], v[30:31], v[226:227]
	v_pk_add_f32 v[28:29], v[28:29], v[224:225]
	s_waitcnt vmcnt(6)
	v_pk_add_f32 v[42:43], v[42:43], v[230:231]
	v_pk_add_f32 v[32:33], v[32:33], v[228:229]
	s_waitcnt vmcnt(5)
	v_pk_add_f32 v[46:47], v[46:47], v[234:235]
	v_pk_add_f32 v[44:45], v[44:45], v[232:233]
	s_waitcnt vmcnt(4)
	v_pk_add_f32 v[2:3], v[2:3], v[238:239]
	v_pk_add_f32 v[0:1], v[0:1], v[236:237]
	s_lshl_b64 s[0:1], s[0:1], 12
	s_waitcnt vmcnt(3)
	v_pk_add_f32 v[30:31], v[30:31], v[26:27]
	v_pk_add_f32 v[28:29], v[28:29], v[24:25]
	s_waitcnt vmcnt(2)
	v_pk_add_f32 v[26:27], v[42:43], v[40:41]
	v_pk_add_f32 v[24:25], v[32:33], v[38:39]
	s_waitcnt vmcnt(1)
	v_pk_add_f32 v[22:23], v[46:47], v[22:23]
	v_pk_add_f32 v[20:21], v[44:45], v[20:21]
	s_waitcnt vmcnt(0)
	v_pk_add_f32 v[2:3], v[2:3], v[36:37]
	v_pk_add_f32 v[0:1], v[0:1], v[34:35]
	v_lshl_add_u64 v[32:33], v[64:65], 0, s[0:1]
	global_store_dwordx4 v[32:33], v[28:31], off
	global_store_dwordx4 v[32:33], v[24:27], off offset:1024
	global_store_dwordx4 v[32:33], v[20:23], off offset:2048
	global_store_dwordx4 v[32:33], v[0:3], off offset:3072
	s_branch .LBB0_2099
